# MLA attention loop rewritten by hand: software-pipelined (QK of tile t+1 overlaps softmax of tile t), K staged one tile ahead
# speedup vs baseline: 1.0405x; 1.0405x over previous
; #define LAS __attribute__((address_space(3)))
; __device__ __forceinline__ void mla_unit(int h, int qb, const bf16_t* __restrict__ Qm, const bf16_t* __restrict__ Km, const bf16_t* __restrict__ Kr, const bf16_t* __restrict__ Vm, bf16_t* ZM, LAS char* lds) {
;     int tid_ = threadIdx.x; asm volatile("" : "+v"(tid_)); const int tid = tid_, lane = tid & 63, r32 = lane & 31, hi = lane >> 5; const int wid = __builtin_amdgcn_readfirstlane(tid >> 6);
;     const int q0 = qb * 256, qrow = q0 + wid * 32 + r32;
;     bf16x8 qf[6];
; #pragma unroll
;     for (int s = 0; s < 6; ++s) qf[s] = *(const bf16x8*)(Qm + (size_t)qrow * 1536 + h * 96 + 16 * s + 8 * hi);
;     const int NT = (q0 + 256) / 64;
;     const int srow = tid >> 3, sch = tid & 7, rrow = (tid & 255) >> 2, rch = tid & 3;
;     const bf16_t* kn_src = Km + (size_t)srow * 1024 + h * 64 + sch * 8;
;     const bf16_t* v_src = Vm + (size_t)srow * 1024 + h * 64 + sch * 8;
;     const bf16_t* kr_src = Kr + (size_t)rrow * 32 + rch * 8;
;     const int kn_dst = srow * KP + sch * 16, kr_dst = rrow * KP + 128 + rch * 16, v_dst = KBUF + srow * VP + sch * 16;
;     u32x4 gknA, gkrA, gvA, gknB, gkrB, gvB;
;     gknA = *(const u32x4*)kn_src; gvA = *(const u32x4*)v_src; gkrA = *(const u32x4*)kr_src;
;     *(LAS u32x4*)(lds + kn_dst) = gknA; *(LAS u32x4*)(lds + v_dst) = gvA; if (tid < 256) *(LAS u32x4*)(lds + kr_dst) = gkrA;
;     gknB = *(const u32x4*)(kn_src + (size_t)64 * 1024); gvB = *(const u32x4*)(v_src + (size_t)64 * 1024); gkrB = *(const u32x4*)(kr_src + (size_t)64 * 32);
;     __syncthreads();
;     float l = 0.f; f32x16 o0 = {}, o1 = {};
;     const int ka_off = r32 * KP + hi * 16;
;     const int i16 = lane & 15, dg = (lane >> 4) & 1;
;     const int va_off = KBUF + (4 * hi + (i16 >> 2)) * VP + (16 * dg + 4 * (i16 & 3)) * 2;
;     float mref = 0.f; f32x16 negm = {};
.LBB0_750:
	v_mov_b32_e32 v4, v196
	s_lshl_b32 s27, s26, 8
	v_readfirstlane_b32 s4, v4
	s_ashr_i32 s39, s4, 6
	s_lshl_b32 s4, s39, 5
	v_and_b32_e32 v6, 31, v4
	s_add_i32 s4, s4, s27
	v_or_b32_e32 v188, s4, v6
	v_mov_b64_e32 v[2:3], s[8:9]
	s_ashr_i32 s6, s38, 4
	v_mad_i64_i32 v[2:3], s[4:5], v188, s95, v[2:3]
	s_mul_i32 s4, s6, 0x60
	v_bfe_u32 v5, v4, 5, 1
	s_ashr_i32 s5, s4, 31
	v_lshl_add_u64 v[2:3], s[4:5], 1, v[2:3]
	v_lshlrev_b32_e32 v0, 4, v5
	v_ashrrev_i32_e32 v16, 3, v4
	v_lshl_add_u64 v[2:3], v[2:3], 0, v[0:1]
	v_ashrrev_i32_e32 v17, 31, v16
	s_lshl_b32 s24, s6, 6
	global_load_dwordx4 v[96:99], v[2:3], off
	global_load_dwordx4 v[100:103], v[2:3], off offset:32
	global_load_dwordx4 v[104:107], v[2:3], off offset:64
	global_load_dwordx4 v[108:111], v[2:3], off offset:96
	global_load_dwordx4 v[112:115], v[2:3], off offset:128
	global_load_dwordx4 v[116:119], v[2:3], off offset:160
	v_lshlrev_b64 v[8:9], 11, v[16:17]
	s_ashr_i32 s25, s24, 31
	v_lshl_add_u64 v[10:11], s[14:15], 0, v[8:9]
	s_lshl_b64 s[4:5], s[24:25], 1
	v_lshlrev_b32_e32 v2, 4, v4
	v_lshl_add_u64 v[10:11], v[10:11], 0, s[4:5]
	v_and_b32_e32 v0, 0x70, v2
	v_lshl_add_u64 v[8:9], s[18:19], 0, v[8:9]
	v_lshl_add_u64 v[190:191], v[10:11], 0, v[0:1]
	v_lshl_add_u64 v[8:9], v[8:9], 0, s[4:5]
	v_lshl_add_u64 v[192:193], v[8:9], 0, v[0:1]
	global_load_dwordx4 v[120:123], v[190:191], off
	global_load_dwordx4 v[124:127], v[192:193], off
	s_movk_i32 s4, 0xd0
	v_bfe_u32 v3, v4, 2, 6
	v_mad_u64_u32 v[18:19], s[4:5], v16, s4, v[0:1]
	v_lshlrev_b32_e32 v7, 4, v16
	v_and_b32_e32 v2, 48, v2
	v_mul_u32_u24_e32 v0, 0xd0, v3
	v_sub_u32_e32 v7, v18, v7
	v_add_u32_e32 v205, 0, v18
	v_add_u32_e32 v206, 0, v7
	v_add_u32_e32 v207, v2, v0
	v_lshlrev_b32_e32 v0, 6, v3
	v_add_u32_e32 v0, v0, v2
	v_lshl_add_u64 v[194:195], s[16:17], 0, v[0:1]
	global_load_dwordx4 v[128:131], v[194:195], off
	s_mov_b64 s[6:7], 0x20000
	v_lshl_add_u64 v[242:243], v[190:191], 0, s[6:7]
	s_mov_b64 s[6:7], 0x1000
	v_lshl_add_u64 v[244:245], v[194:195], 0, s[6:7]
	global_load_dwordx4 v[164:167], v[242:243], off
	global_load_dwordx4 v[168:171], v[244:245], off
	v_lshrrev_b32_e32 v0, 2, v4
	v_lshlrev_b32_e32 v208, 2, v5
	v_mul_u32_u24_e32 v2, 0xd0, v6
	v_lshl_add_u32 v210, v5, 4, v2
	v_and_b32_e32 v2, 16, v4
	v_and_or_b32 v0, v0, 3, v208
	v_lshlrev_b32_e32 v3, 2, v4
	v_mul_u32_u24_e32 v0, 0xc0, v0
	v_and_or_b32 v2, v3, 12, v2
	v_lshl_or_b32 v211, v2, 1, v0
	v_ashrrev_i32_e32 v189, 31, v188
	s_addk_i32 s27, 0x100
	s_lshr_b32 s40, s27, 6
	s_add_i32 s44, s40, -1
	s_add_i32 s64, s40, -4
	s_lshr_b32 s45, s39, 1
	s_add_i32 s45, s45, s40
	s_add_i32 s45, s45, -3
	s_mov_b32 s65, 0
	v_mov_b32_e32 v209, 0
	v_mov_b32_e32 v212, 0
	v_mov_b32_e32 v48, 0
	v_mov_b32_e32 v49, 0
	v_mov_b32_e32 v50, 0
	v_mov_b32_e32 v51, 0
	v_mov_b32_e32 v52, 0
	v_mov_b32_e32 v53, 0
	v_mov_b32_e32 v54, 0
	v_mov_b32_e32 v55, 0
	v_mov_b32_e32 v56, 0
	v_mov_b32_e32 v57, 0
	v_mov_b32_e32 v58, 0
	v_mov_b32_e32 v59, 0
	v_mov_b32_e32 v60, 0
	v_mov_b32_e32 v61, 0
	v_mov_b32_e32 v62, 0
	v_mov_b32_e32 v63, 0
	v_mov_b32_e32 v32, 0
	v_mov_b32_e32 v33, 0
	v_mov_b32_e32 v34, 0
	v_mov_b32_e32 v35, 0
	v_mov_b32_e32 v36, 0
	v_mov_b32_e32 v37, 0
	v_mov_b32_e32 v38, 0
	v_mov_b32_e32 v39, 0
	v_mov_b32_e32 v40, 0
	v_mov_b32_e32 v41, 0
	v_mov_b32_e32 v42, 0
	v_mov_b32_e32 v43, 0
	v_mov_b32_e32 v44, 0
	v_mov_b32_e32 v45, 0
	v_mov_b32_e32 v46, 0
	v_mov_b32_e32 v47, 0
	v_mov_b32_e32 v16, 0
	v_mov_b32_e32 v17, 0
	v_mov_b32_e32 v18, 0
	v_mov_b32_e32 v19, 0
	v_mov_b32_e32 v20, 0
	v_mov_b32_e32 v21, 0
	v_mov_b32_e32 v22, 0
	v_mov_b32_e32 v23, 0
	v_mov_b32_e32 v24, 0
	v_mov_b32_e32 v25, 0
	v_mov_b32_e32 v26, 0
	v_mov_b32_e32 v27, 0
	v_mov_b32_e32 v28, 0
	v_mov_b32_e32 v29, 0
	v_mov_b32_e32 v30, 0
	v_mov_b32_e32 v31, 0
	s_waitcnt vmcnt(0)
	ds_write_b128 v205, v[120:123] offset:0
	ds_write_b128 v206, v[124:127] offset:13312
	ds_write_b128 v207, v[128:131] offset:128
	ds_write_b128 v205, v[164:167] offset:25600
	ds_write_b128 v207, v[168:171] offset:25728
	s_waitcnt lgkmcnt(0)
	s_barrier
	s_mov_b64 s[6:7], 0x40000
	v_lshl_add_u64 v[242:243], v[190:191], 0, s[6:7]
	s_mov_b64 s[6:7], 0x20000
	v_lshl_add_u64 v[246:247], v[192:193], 0, s[6:7]
	s_mov_b64 s[6:7], 0x2000
	v_lshl_add_u64 v[244:245], v[194:195], 0, s[6:7]
	global_load_dwordx4 v[120:123], v[242:243], off
	global_load_dwordx4 v[124:127], v[246:247], off
	global_load_dwordx4 v[128:131], v[244:245], off
	ds_read_b128 v[164:167], v210 offset:0
	ds_read_b128 v[168:171], v210 offset:32
	ds_read_b128 v[172:175], v210 offset:64
	ds_read_b128 v[214:217], v210 offset:96
	ds_read_b128 v[218:221], v210 offset:128
	ds_read_b128 v[222:225], v210 offset:160
	s_waitcnt lgkmcnt(5)
	v_mfma_f32_32x32x16_bf16 v[64:79], v[164:167], v[96:99], v[48:63]
	ds_read_b128 v[164:167], v210 offset:6656
	s_waitcnt lgkmcnt(5)
	v_mfma_f32_32x32x16_bf16 v[64:79], v[168:171], v[100:103], v[64:79]
	ds_read_b128 v[168:171], v210 offset:6688
	s_waitcnt lgkmcnt(5)
	v_mfma_f32_32x32x16_bf16 v[64:79], v[172:175], v[104:107], v[64:79]
	ds_read_b128 v[172:175], v210 offset:6720
	s_waitcnt lgkmcnt(5)
	v_mfma_f32_32x32x16_bf16 v[64:79], v[214:217], v[108:111], v[64:79]
	ds_read_b128 v[214:217], v210 offset:6752
	s_waitcnt lgkmcnt(5)
	v_mfma_f32_32x32x16_bf16 v[64:79], v[218:221], v[112:115], v[64:79]
	ds_read_b128 v[218:221], v210 offset:6784
	s_waitcnt lgkmcnt(5)
	v_mfma_f32_32x32x16_bf16 v[64:79], v[222:225], v[116:119], v[64:79]
	ds_read_b128 v[222:225], v210 offset:6816
	s_waitcnt lgkmcnt(5)
	v_mfma_f32_32x32x16_bf16 v[80:95], v[164:167], v[96:99], v[48:63]
	s_waitcnt lgkmcnt(4)
	v_mfma_f32_32x32x16_bf16 v[80:95], v[168:171], v[100:103], v[80:95]
	s_waitcnt lgkmcnt(3)
	v_mfma_f32_32x32x16_bf16 v[80:95], v[172:175], v[104:107], v[80:95]
	s_waitcnt lgkmcnt(2)
	v_mfma_f32_32x32x16_bf16 v[80:95], v[214:217], v[108:111], v[80:95]
	s_waitcnt lgkmcnt(1)
	v_mfma_f32_32x32x16_bf16 v[80:95], v[218:221], v[112:115], v[80:95]
	s_waitcnt lgkmcnt(0)
	v_mfma_f32_32x32x16_bf16 v[80:95], v[222:225], v[116:119], v[80:95]
	s_nop 7
	s_nop 4
	s_cmp_lg_u32 s64, 0
	s_cbranch_scc1 .Lmla_p_nomask
	v_sub_u32_e32 v0, v188, v208
	s_nop 0
	v_cmp_le_i32_e32 vcc, 0, v0
	v_cmp_le_i32_e64 s[6:7], 1, v0
	s_nop 0
	v_cndmask_b32_e32 v64, v204, v64, vcc
	v_cndmask_b32_e64 v65, v204, v65, s[6:7]
	v_cmp_le_i32_e32 vcc, 2, v0
	v_cmp_le_i32_e64 s[6:7], 3, v0
	s_nop 0
	v_cndmask_b32_e32 v66, v204, v66, vcc
	v_cndmask_b32_e64 v67, v204, v67, s[6:7]
	v_cmp_le_i32_e32 vcc, 8, v0
	v_cmp_le_i32_e64 s[6:7], 9, v0
	s_nop 0
	v_cndmask_b32_e32 v68, v204, v68, vcc
	v_cndmask_b32_e64 v69, v204, v69, s[6:7]
	v_cmp_le_i32_e32 vcc, 10, v0
	v_cmp_le_i32_e64 s[6:7], 11, v0
	s_nop 0
	v_cndmask_b32_e32 v70, v204, v70, vcc
	v_cndmask_b32_e64 v71, v204, v71, s[6:7]
	v_cmp_le_i32_e32 vcc, 16, v0
	v_cmp_le_i32_e64 s[6:7], 17, v0
	s_nop 0
	v_cndmask_b32_e32 v72, v204, v72, vcc
	v_cndmask_b32_e64 v73, v204, v73, s[6:7]
	v_cmp_le_i32_e32 vcc, 18, v0
	v_cmp_le_i32_e64 s[6:7], 19, v0
	s_nop 0
	v_cndmask_b32_e32 v74, v204, v74, vcc
	v_cndmask_b32_e64 v75, v204, v75, s[6:7]
	v_cmp_le_i32_e32 vcc, 24, v0
	v_cmp_le_i32_e64 s[6:7], 25, v0
	s_nop 0
	v_cndmask_b32_e32 v76, v204, v76, vcc
	v_cndmask_b32_e64 v77, v204, v77, s[6:7]
	v_cmp_le_i32_e32 vcc, 26, v0
	v_cmp_le_i32_e64 s[6:7], 27, v0
	s_nop 0
	v_cndmask_b32_e32 v78, v204, v78, vcc
	v_cndmask_b32_e64 v79, v204, v79, s[6:7]
	v_cmp_le_i32_e32 vcc, 32, v0
	v_cmp_le_i32_e64 s[6:7], 33, v0
	s_nop 0
	v_cndmask_b32_e32 v80, v204, v80, vcc
	v_cndmask_b32_e64 v81, v204, v81, s[6:7]
	v_cmp_le_i32_e32 vcc, 34, v0
	v_cmp_le_i32_e64 s[6:7], 35, v0
	s_nop 0
	v_cndmask_b32_e32 v82, v204, v82, vcc
	v_cndmask_b32_e64 v83, v204, v83, s[6:7]
	v_cmp_le_i32_e32 vcc, 40, v0
	v_cmp_le_i32_e64 s[6:7], 41, v0
	s_nop 0
	v_cndmask_b32_e32 v84, v204, v84, vcc
	v_cndmask_b32_e64 v85, v204, v85, s[6:7]
	v_cmp_le_i32_e32 vcc, 42, v0
	v_cmp_le_i32_e64 s[6:7], 43, v0
	s_nop 0
	v_cndmask_b32_e32 v86, v204, v86, vcc
	v_cndmask_b32_e64 v87, v204, v87, s[6:7]
	v_cmp_le_i32_e32 vcc, 48, v0
	v_cmp_le_i32_e64 s[6:7], 49, v0
	s_nop 0
	v_cndmask_b32_e32 v88, v204, v88, vcc
	v_cndmask_b32_e64 v89, v204, v89, s[6:7]
	v_cmp_le_i32_e32 vcc, 50, v0
	v_cmp_le_i32_e64 s[6:7], 51, v0
	s_nop 0
	v_cndmask_b32_e32 v90, v204, v90, vcc
	v_cndmask_b32_e64 v91, v204, v91, s[6:7]
	v_cmp_le_i32_e32 vcc, 56, v0
	v_cmp_le_i32_e64 s[6:7], 57, v0
	s_nop 0
	v_cndmask_b32_e32 v92, v204, v92, vcc
	v_cndmask_b32_e64 v93, v204, v93, s[6:7]
	v_cmp_le_i32_e32 vcc, 58, v0
	v_cmp_le_i32_e64 s[6:7], 59, v0
	s_nop 0
	v_cndmask_b32_e32 v94, v204, v94, vcc
	v_cndmask_b32_e64 v95, v204, v95, s[6:7]
.Lmla_p_nomask:
	v_max3_f32 v251, v64, v65, v66
	v_max3_f32 v251, v251, v67, v68
	v_max3_f32 v251, v251, v69, v70
	v_max3_f32 v251, v251, v71, v72
	v_max3_f32 v251, v251, v73, v74
	v_max3_f32 v251, v251, v75, v76
	v_max3_f32 v251, v251, v77, v78
	v_max_f32_e32 v251, v251, v79
	v_max3_f32 v252, v80, v81, v82
	v_max3_f32 v252, v252, v83, v84
	v_max3_f32 v252, v252, v85, v86
	v_max3_f32 v252, v252, v87, v88
	v_max3_f32 v252, v252, v89, v90
	v_max3_f32 v252, v252, v91, v92
	v_max3_f32 v252, v252, v93, v94
	v_max_f32_e32 v252, v252, v95
	v_max_f32_e32 v251, v251, v252
	v_mov_b32_e32 v252, v251
	s_nop 1
	v_permlane32_swap_b32_e32 v251, v252
	v_max_f32_e32 v251, v251, v252
	v_mov_b32_e32 v212, v251
	v_sub_f32_e32 v64, v64, v251
	v_sub_f32_e32 v65, v65, v251
	v_sub_f32_e32 v66, v66, v251
	v_sub_f32_e32 v67, v67, v251
	v_sub_f32_e32 v68, v68, v251
	v_sub_f32_e32 v69, v69, v251
	v_sub_f32_e32 v70, v70, v251
	v_sub_f32_e32 v71, v71, v251
	v_sub_f32_e32 v72, v72, v251
	v_sub_f32_e32 v73, v73, v251
	v_sub_f32_e32 v74, v74, v251
	v_sub_f32_e32 v75, v75, v251
	v_sub_f32_e32 v76, v76, v251
	v_sub_f32_e32 v77, v77, v251
	v_sub_f32_e32 v78, v78, v251
	v_sub_f32_e32 v79, v79, v251
	v_sub_f32_e32 v80, v80, v251
	v_sub_f32_e32 v81, v81, v251
	v_sub_f32_e32 v82, v82, v251
	v_sub_f32_e32 v83, v83, v251
	v_sub_f32_e32 v84, v84, v251
	v_sub_f32_e32 v85, v85, v251
	v_sub_f32_e32 v86, v86, v251
	v_sub_f32_e32 v87, v87, v251
	v_sub_f32_e32 v88, v88, v251
	v_sub_f32_e32 v89, v89, v251
	v_sub_f32_e32 v90, v90, v251
	v_sub_f32_e32 v91, v91, v251
	v_sub_f32_e32 v92, v92, v251
	v_sub_f32_e32 v93, v93, v251
	v_sub_f32_e32 v94, v94, v251
	v_sub_f32_e32 v95, v95, v251
	v_xor_b32_e32 v48, 0x80000000, v251
	v_mov_b32_e32 v49, v48
	v_mov_b32_e32 v50, v48
	v_mov_b32_e32 v51, v48
	v_mov_b32_e32 v52, v48
	v_mov_b32_e32 v53, v48
	v_mov_b32_e32 v54, v48
	v_mov_b32_e32 v55, v48
	v_mov_b32_e32 v56, v48
	v_mov_b32_e32 v57, v48
	v_mov_b32_e32 v58, v48
	v_mov_b32_e32 v59, v48
	v_mov_b32_e32 v60, v48
	v_mov_b32_e32 v61, v48
	v_mov_b32_e32 v62, v48
	v_mov_b32_e32 v63, v48
	s_waitcnt lgkmcnt(0)
	s_barrier
.Lmla_loop:
.Lmla_it0:
	s_add_i32 s42, s65, 3
	s_min_u32 s42, s42, s44
	s_lshl_b64 s[6:7], s[42:43], 17
	v_lshl_add_u64 v[242:243], v[190:191], 0, s[6:7]
	s_lshl_b64 s[6:7], s[42:43], 12
	v_lshl_add_u64 v[244:245], v[194:195], 0, s[6:7]
	s_add_i32 s42, s65, 2
	s_min_u32 s42, s42, s44
	s_lshl_b64 s[6:7], s[42:43], 17
	v_lshl_add_u64 v[246:247], v[192:193], 0, s[6:7]
	global_load_dwordx4 v[6:9], v[242:243], off
	global_load_dwordx4 v[10:13], v[246:247], off
	global_load_dwordx4 v[2:5], v[244:245], off
	s_cmp_ge_u32 s65, s45
	s_cbranch_scc1 .Lmla_skip0
	s_add_i32 s41, s65, 1
	s_cmp_ge_u32 s41, s64
	s_cselect_b32 s7, 1, 0
	s_cmp_lt_u32 s41, s45
	s_cselect_b32 s26, 1, 0
	s_and_b32 s56, s7, s26
	s_lshl_b32 s27, s41, 6
	ds_read_b128 v[164:167], v210 offset:25600
	ds_read_b128 v[168:171], v210 offset:25632
	ds_read_b128 v[172:175], v210 offset:25664
	ds_read_b128 v[214:217], v210 offset:25696
	ds_read_b128 v[218:221], v210 offset:25728
	ds_read_b128 v[222:225], v210 offset:25760
	v_exp_f32_e32 v64, v64
	v_exp_f32_e32 v65, v65
	v_exp_f32_e32 v66, v66
	v_exp_f32_e32 v67, v67
	s_waitcnt lgkmcnt(5)
	v_mfma_f32_32x32x16_bf16 v[132:147], v[164:167], v[96:99], v[48:63]
	ds_read_b128 v[164:167], v210 offset:32256
	v_add_f32_e32 v14, v64, v65
	v_add_f32_e32 v15, v66, v67
	v_exp_f32_e32 v68, v68
	v_exp_f32_e32 v69, v69
	s_waitcnt lgkmcnt(5)
	v_mfma_f32_32x32x16_bf16 v[132:147], v[168:171], v[100:103], v[132:147]
	ds_read_b128 v[168:171], v210 offset:32288
	v_exp_f32_e32 v70, v70
	v_exp_f32_e32 v71, v71
	v_add_f32_e32 v14, v14, v15
	v_add_f32_e32 v15, v68, v69
	s_waitcnt lgkmcnt(5)
	v_mfma_f32_32x32x16_bf16 v[132:147], v[172:175], v[104:107], v[132:147]
	ds_read_b128 v[172:175], v210 offset:32320
	v_add_f32_e32 v213, v70, v71
	v_cvt_pk_bf16_f32 v64, v64, v65
	v_cvt_pk_bf16_f32 v65, v66, v67
	v_cvt_pk_bf16_f32 v66, v68, v69
	v_cvt_pk_bf16_f32 v67, v70, v71
	s_waitcnt lgkmcnt(5)
	v_mfma_f32_32x32x16_bf16 v[132:147], v[214:217], v[108:111], v[132:147]
	ds_read_b128 v[214:217], v210 offset:32352
	v_exp_f32_e32 v72, v72
	v_exp_f32_e32 v73, v73
	v_exp_f32_e32 v74, v74
	v_exp_f32_e32 v75, v75
	s_waitcnt lgkmcnt(5)
	v_mfma_f32_32x32x16_bf16 v[132:147], v[218:221], v[112:115], v[132:147]
	ds_read_b128 v[218:221], v210 offset:32384
	v_add_f32_e32 v14, v14, v15
	v_add_f32_e32 v14, v14, v213
	v_exp_f32_e32 v76, v76
	v_exp_f32_e32 v77, v77
	s_waitcnt lgkmcnt(5)
	v_mfma_f32_32x32x16_bf16 v[132:147], v[222:225], v[116:119], v[132:147]
	ds_read_b128 v[222:225], v210 offset:32416
	v_exp_f32_e32 v78, v78
	v_exp_f32_e32 v79, v79
	v_add_f32_e32 v15, v72, v73
	v_add_f32_e32 v213, v74, v75
	s_waitcnt lgkmcnt(5)
	v_mfma_f32_32x32x16_bf16 v[148:163], v[164:167], v[96:99], v[48:63]
	ds_read_b64_tr_b16 v[226:227], v211 offset:13312
	ds_read_b64_tr_b16 v[228:229], v211 offset:14848
	v_add_f32_e32 v248, v76, v77
	v_add_f32_e32 v249, v78, v79
	v_cvt_pk_bf16_f32 v68, v72, v73
	v_cvt_pk_bf16_f32 v69, v74, v75
	v_cvt_pk_bf16_f32 v70, v76, v77
	v_cvt_pk_bf16_f32 v71, v78, v79
	s_waitcnt lgkmcnt(6)
	v_mfma_f32_32x32x16_bf16 v[148:163], v[168:171], v[100:103], v[148:163]
	ds_read_b64_tr_b16 v[230:231], v211 offset:13376
	ds_read_b64_tr_b16 v[232:233], v211 offset:14912
	v_add_f32_e32 v15, v15, v213
	v_add_f32_e32 v248, v248, v249
	v_exp_f32_e32 v80, v80
	v_exp_f32_e32 v81, v81
	s_waitcnt lgkmcnt(7)
	v_mfma_f32_32x32x16_bf16 v[148:163], v[172:175], v[104:107], v[148:163]
	ds_read_b64_tr_b16 v[234:235], v211 offset:16384
	ds_read_b64_tr_b16 v[236:237], v211 offset:17920
	v_exp_f32_e32 v82, v82
	v_exp_f32_e32 v83, v83
	v_add_f32_e32 v14, v14, v15
	v_add_f32_e32 v14, v14, v248
	s_waitcnt lgkmcnt(8)
	v_mfma_f32_32x32x16_bf16 v[148:163], v[214:217], v[108:111], v[148:163]
	ds_read_b64_tr_b16 v[238:239], v211 offset:16448
	ds_read_b64_tr_b16 v[240:241], v211 offset:17984
	v_add_f32_e32 v15, v80, v81
	v_add_f32_e32 v213, v82, v83
	v_exp_f32_e32 v84, v84
	v_exp_f32_e32 v85, v85
	s_waitcnt lgkmcnt(9)
	v_mfma_f32_32x32x16_bf16 v[148:163], v[218:221], v[112:115], v[148:163]
	v_exp_f32_e32 v86, v86
	v_exp_f32_e32 v87, v87
	v_add_f32_e32 v15, v15, v213
	v_add_f32_e32 v213, v84, v85
	s_waitcnt lgkmcnt(8)
	v_mfma_f32_32x32x16_bf16 v[148:163], v[222:225], v[116:119], v[148:163]
	v_add_f32_e32 v248, v86, v87
	v_cvt_pk_bf16_f32 v80, v80, v81
	v_cvt_pk_bf16_f32 v81, v82, v83
	v_cvt_pk_bf16_f32 v82, v84, v85
	v_cvt_pk_bf16_f32 v83, v86, v87
	s_waitcnt lgkmcnt(6)
	v_mfma_f32_32x32x16_bf16 v[32:47], v[226:229], v[64:67], v[32:47]
	ds_read_b64_tr_b16 v[226:227], v211 offset:19456
	ds_read_b64_tr_b16 v[228:229], v211 offset:20992
	v_exp_f32_e32 v88, v88
	v_exp_f32_e32 v89, v89
	v_exp_f32_e32 v90, v90
	v_exp_f32_e32 v91, v91
	s_waitcnt lgkmcnt(6)
	v_mfma_f32_32x32x16_bf16 v[16:31], v[230:233], v[64:67], v[16:31]
	ds_read_b64_tr_b16 v[230:231], v211 offset:19520
	ds_read_b64_tr_b16 v[232:233], v211 offset:21056
	v_add_f32_e32 v213, v213, v248
	v_add_f32_e32 v15, v15, v213
	v_exp_f32_e32 v92, v92
	v_exp_f32_e32 v93, v93
	s_waitcnt lgkmcnt(6)
	v_mfma_f32_32x32x16_bf16 v[32:47], v[234:237], v[68:71], v[32:47]
	ds_read_b64_tr_b16 v[234:235], v211 offset:22528
	ds_read_b64_tr_b16 v[236:237], v211 offset:24064
	v_exp_f32_e32 v94, v94
	v_exp_f32_e32 v95, v95
	v_add_f32_e32 v213, v88, v89
	v_add_f32_e32 v248, v90, v91
	s_waitcnt lgkmcnt(6)
	v_mfma_f32_32x32x16_bf16 v[16:31], v[238:241], v[68:71], v[16:31]
	ds_read_b64_tr_b16 v[238:239], v211 offset:22592
	ds_read_b64_tr_b16 v[240:241], v211 offset:24128
	s_cmp_lg_u32 s56, 0
	s_cbranch_scc1 .Lmla_mask0
.Lmla_maskret0:
	v_add_f32_e32 v249, v92, v93
	v_add_f32_e32 v250, v94, v95
	v_cvt_pk_bf16_f32 v84, v88, v89
	v_cvt_pk_bf16_f32 v85, v90, v91
	v_cvt_pk_bf16_f32 v86, v92, v93
	v_cvt_pk_bf16_f32 v87, v94, v95
	s_waitcnt lgkmcnt(6)
	v_mfma_f32_32x32x16_bf16 v[32:47], v[226:229], v[80:83], v[32:47]
	v_add_f32_e32 v213, v213, v248
	v_add_f32_e32 v249, v249, v250
	v_add_f32_e32 v14, v14, v15
	v_max3_f32 v251, v132, v133, v134
	v_max3_f32 v251, v251, v135, v136
	s_waitcnt lgkmcnt(4)
	v_mfma_f32_32x32x16_bf16 v[16:31], v[230:233], v[80:83], v[16:31]
	s_waitcnt vmcnt(3)
	ds_write_b128 v205, v[120:123] offset:0
	ds_write_b128 v206, v[124:127] offset:38912
	v_add_f32_e32 v213, v213, v249
	v_add_f32_e32 v14, v14, v213
	v_add_f32_e32 v209, v209, v14
	v_max3_f32 v251, v251, v137, v138
	v_max3_f32 v251, v251, v139, v140
	v_max3_f32 v251, v251, v141, v142
	s_waitcnt lgkmcnt(4)
	v_mfma_f32_32x32x16_bf16 v[32:47], v[234:237], v[84:87], v[32:47]
	v_max3_f32 v251, v251, v143, v144
	v_max3_f32 v251, v251, v145, v146
	v_max_f32_e32 v251, v251, v147
	v_max3_f32 v252, v148, v149, v150
	v_max3_f32 v252, v252, v151, v152
	s_waitcnt lgkmcnt(2)
	v_mfma_f32_32x32x16_bf16 v[16:31], v[238:241], v[84:87], v[16:31]
	ds_write_b128 v207, v[128:131] offset:128
	v_max3_f32 v252, v252, v153, v154
	v_max3_f32 v252, v252, v155, v156
	v_max3_f32 v252, v252, v157, v158
	v_max3_f32 v252, v252, v159, v160
	v_max3_f32 v252, v252, v161, v162
	v_max_f32_e32 v252, v252, v163
	v_max_f32_e32 v251, v251, v252
	v_mov_b32_e32 v252, v251
	s_nop 1
	v_permlane32_swap_b32_e32 v251, v252
	v_max_f32_e32 v251, v251, v252
	v_cmp_lt_f32_e32 vcc, 0x41000000, v251
	s_cmp_lg_u32 s26, 0
	s_cbranch_scc0 .Lmla_nr0
	s_cbranch_vccnz .Lmla_rare0
.Lmla_nr0:
	s_waitcnt lgkmcnt(0)
	s_barrier
.Lmla_end0:
.Lmla_it1:
	s_add_i32 s66, s65, 1
	s_add_i32 s42, s66, 3
	s_min_u32 s42, s42, s44
	s_lshl_b64 s[6:7], s[42:43], 17
	v_lshl_add_u64 v[242:243], v[190:191], 0, s[6:7]
	s_lshl_b64 s[6:7], s[42:43], 12
	v_lshl_add_u64 v[244:245], v[194:195], 0, s[6:7]
	s_add_i32 s42, s66, 2
	s_min_u32 s42, s42, s44
	s_lshl_b64 s[6:7], s[42:43], 17
	v_lshl_add_u64 v[246:247], v[192:193], 0, s[6:7]
	global_load_dwordx4 v[120:123], v[242:243], off
	global_load_dwordx4 v[124:127], v[246:247], off
	global_load_dwordx4 v[128:131], v[244:245], off
	s_cmp_ge_u32 s66, s45
	s_cbranch_scc1 .Lmla_skip1
	s_add_i32 s41, s66, 1
	s_cmp_ge_u32 s41, s64
	s_cselect_b32 s7, 1, 0
	s_cmp_lt_u32 s41, s45
	s_cselect_b32 s26, 1, 0
	s_and_b32 s56, s7, s26
	s_lshl_b32 s27, s41, 6
	ds_read_b128 v[164:167], v210 offset:0
	ds_read_b128 v[168:171], v210 offset:32
	ds_read_b128 v[172:175], v210 offset:64
	ds_read_b128 v[214:217], v210 offset:96
	ds_read_b128 v[218:221], v210 offset:128
	ds_read_b128 v[222:225], v210 offset:160
	v_exp_f32_e32 v132, v132
	v_exp_f32_e32 v133, v133
	v_exp_f32_e32 v134, v134
	v_exp_f32_e32 v135, v135
	s_waitcnt lgkmcnt(5)
	v_mfma_f32_32x32x16_bf16 v[64:79], v[164:167], v[96:99], v[48:63]
	ds_read_b128 v[164:167], v210 offset:6656
	v_add_f32_e32 v14, v132, v133
	v_add_f32_e32 v15, v134, v135
	v_exp_f32_e32 v136, v136
	v_exp_f32_e32 v137, v137
	s_waitcnt lgkmcnt(5)
	v_mfma_f32_32x32x16_bf16 v[64:79], v[168:171], v[100:103], v[64:79]
	ds_read_b128 v[168:171], v210 offset:6688
	v_exp_f32_e32 v138, v138
	v_exp_f32_e32 v139, v139
	v_add_f32_e32 v14, v14, v15
	v_add_f32_e32 v15, v136, v137
	s_waitcnt lgkmcnt(5)
	v_mfma_f32_32x32x16_bf16 v[64:79], v[172:175], v[104:107], v[64:79]
	ds_read_b128 v[172:175], v210 offset:6720
	v_add_f32_e32 v213, v138, v139
	v_cvt_pk_bf16_f32 v132, v132, v133
	v_cvt_pk_bf16_f32 v133, v134, v135
	v_cvt_pk_bf16_f32 v134, v136, v137
	v_cvt_pk_bf16_f32 v135, v138, v139
	s_waitcnt lgkmcnt(5)
	v_mfma_f32_32x32x16_bf16 v[64:79], v[214:217], v[108:111], v[64:79]
	ds_read_b128 v[214:217], v210 offset:6752
	v_exp_f32_e32 v140, v140
	v_exp_f32_e32 v141, v141
	v_exp_f32_e32 v142, v142
	v_exp_f32_e32 v143, v143
	s_waitcnt lgkmcnt(5)
	v_mfma_f32_32x32x16_bf16 v[64:79], v[218:221], v[112:115], v[64:79]
	ds_read_b128 v[218:221], v210 offset:6784
	v_add_f32_e32 v14, v14, v15
	v_add_f32_e32 v14, v14, v213
	v_exp_f32_e32 v144, v144
	v_exp_f32_e32 v145, v145
	s_waitcnt lgkmcnt(5)
	v_mfma_f32_32x32x16_bf16 v[64:79], v[222:225], v[116:119], v[64:79]
	ds_read_b128 v[222:225], v210 offset:6816
	v_exp_f32_e32 v146, v146
	v_exp_f32_e32 v147, v147
	v_add_f32_e32 v15, v140, v141
	v_add_f32_e32 v213, v142, v143
	s_waitcnt lgkmcnt(5)
	v_mfma_f32_32x32x16_bf16 v[80:95], v[164:167], v[96:99], v[48:63]
	ds_read_b64_tr_b16 v[226:227], v211 offset:38912
	ds_read_b64_tr_b16 v[228:229], v211 offset:40448
	v_add_f32_e32 v248, v144, v145
	v_add_f32_e32 v249, v146, v147
	v_cvt_pk_bf16_f32 v136, v140, v141
	v_cvt_pk_bf16_f32 v137, v142, v143
	v_cvt_pk_bf16_f32 v138, v144, v145
	v_cvt_pk_bf16_f32 v139, v146, v147
	s_waitcnt lgkmcnt(6)
	v_mfma_f32_32x32x16_bf16 v[80:95], v[168:171], v[100:103], v[80:95]
	ds_read_b64_tr_b16 v[230:231], v211 offset:38976
	ds_read_b64_tr_b16 v[232:233], v211 offset:40512
	v_add_f32_e32 v15, v15, v213
	v_add_f32_e32 v248, v248, v249
	v_exp_f32_e32 v148, v148
	v_exp_f32_e32 v149, v149
	s_waitcnt lgkmcnt(7)
	v_mfma_f32_32x32x16_bf16 v[80:95], v[172:175], v[104:107], v[80:95]
	ds_read_b64_tr_b16 v[234:235], v211 offset:41984
	ds_read_b64_tr_b16 v[236:237], v211 offset:43520
	v_exp_f32_e32 v150, v150
	v_exp_f32_e32 v151, v151
	v_add_f32_e32 v14, v14, v15
	v_add_f32_e32 v14, v14, v248
	s_waitcnt lgkmcnt(8)
	v_mfma_f32_32x32x16_bf16 v[80:95], v[214:217], v[108:111], v[80:95]
	ds_read_b64_tr_b16 v[238:239], v211 offset:42048
	ds_read_b64_tr_b16 v[240:241], v211 offset:43584
	v_add_f32_e32 v15, v148, v149
	v_add_f32_e32 v213, v150, v151
	v_exp_f32_e32 v152, v152
	v_exp_f32_e32 v153, v153
	s_waitcnt lgkmcnt(9)
	v_mfma_f32_32x32x16_bf16 v[80:95], v[218:221], v[112:115], v[80:95]
	v_exp_f32_e32 v154, v154
	v_exp_f32_e32 v155, v155
	v_add_f32_e32 v15, v15, v213
	v_add_f32_e32 v213, v152, v153
	s_waitcnt lgkmcnt(8)
	v_mfma_f32_32x32x16_bf16 v[80:95], v[222:225], v[116:119], v[80:95]
	v_add_f32_e32 v248, v154, v155
	v_cvt_pk_bf16_f32 v148, v148, v149
	v_cvt_pk_bf16_f32 v149, v150, v151
	v_cvt_pk_bf16_f32 v150, v152, v153
	v_cvt_pk_bf16_f32 v151, v154, v155
	s_waitcnt lgkmcnt(6)
	v_mfma_f32_32x32x16_bf16 v[32:47], v[226:229], v[132:135], v[32:47]
	ds_read_b64_tr_b16 v[226:227], v211 offset:45056
	ds_read_b64_tr_b16 v[228:229], v211 offset:46592
	v_exp_f32_e32 v156, v156
	v_exp_f32_e32 v157, v157
	v_exp_f32_e32 v158, v158
	v_exp_f32_e32 v159, v159
	s_waitcnt lgkmcnt(6)
	v_mfma_f32_32x32x16_bf16 v[16:31], v[230:233], v[132:135], v[16:31]
	ds_read_b64_tr_b16 v[230:231], v211 offset:45120
	ds_read_b64_tr_b16 v[232:233], v211 offset:46656
	v_add_f32_e32 v213, v213, v248
	v_add_f32_e32 v15, v15, v213
	v_exp_f32_e32 v160, v160
	v_exp_f32_e32 v161, v161
	s_waitcnt lgkmcnt(6)
	v_mfma_f32_32x32x16_bf16 v[32:47], v[234:237], v[136:139], v[32:47]
	ds_read_b64_tr_b16 v[234:235], v211 offset:48128
	ds_read_b64_tr_b16 v[236:237], v211 offset:49664
	v_exp_f32_e32 v162, v162
	v_exp_f32_e32 v163, v163
	v_add_f32_e32 v213, v156, v157
	v_add_f32_e32 v248, v158, v159
	s_waitcnt lgkmcnt(6)
	v_mfma_f32_32x32x16_bf16 v[16:31], v[238:241], v[136:139], v[16:31]
	ds_read_b64_tr_b16 v[238:239], v211 offset:48192
	ds_read_b64_tr_b16 v[240:241], v211 offset:49728
	s_cmp_lg_u32 s56, 0
	s_cbranch_scc1 .Lmla_mask1
.Lmla_maskret1:
	v_add_f32_e32 v249, v160, v161
	v_add_f32_e32 v250, v162, v163
	v_cvt_pk_bf16_f32 v152, v156, v157
	v_cvt_pk_bf16_f32 v153, v158, v159
	v_cvt_pk_bf16_f32 v154, v160, v161
	v_cvt_pk_bf16_f32 v155, v162, v163
	s_waitcnt lgkmcnt(6)
	v_mfma_f32_32x32x16_bf16 v[32:47], v[226:229], v[148:151], v[32:47]
	v_add_f32_e32 v213, v213, v248
	v_add_f32_e32 v249, v249, v250
	v_add_f32_e32 v14, v14, v15
	v_max3_f32 v251, v64, v65, v66
	v_max3_f32 v251, v251, v67, v68
	s_waitcnt lgkmcnt(4)
	v_mfma_f32_32x32x16_bf16 v[16:31], v[230:233], v[148:151], v[16:31]
	s_waitcnt vmcnt(3)
	ds_write_b128 v205, v[6:9] offset:25600
	ds_write_b128 v206, v[10:13] offset:13312
	v_add_f32_e32 v213, v213, v249
	v_add_f32_e32 v14, v14, v213
	v_add_f32_e32 v209, v209, v14
	v_max3_f32 v251, v251, v69, v70
	v_max3_f32 v251, v251, v71, v72
	v_max3_f32 v251, v251, v73, v74
	s_waitcnt lgkmcnt(4)
	v_mfma_f32_32x32x16_bf16 v[32:47], v[234:237], v[152:155], v[32:47]
	v_max3_f32 v251, v251, v75, v76
	v_max3_f32 v251, v251, v77, v78
	v_max_f32_e32 v251, v251, v79
	v_max3_f32 v252, v80, v81, v82
	v_max3_f32 v252, v252, v83, v84
	s_waitcnt lgkmcnt(2)
	v_mfma_f32_32x32x16_bf16 v[16:31], v[238:241], v[152:155], v[16:31]
	ds_write_b128 v207, v[2:5] offset:25728
	v_max3_f32 v252, v252, v85, v86
	v_max3_f32 v252, v252, v87, v88
	v_max3_f32 v252, v252, v89, v90
	v_max3_f32 v252, v252, v91, v92
	v_max3_f32 v252, v252, v93, v94
	v_max_f32_e32 v252, v252, v95
	v_max_f32_e32 v251, v251, v252
	v_mov_b32_e32 v252, v251
	s_nop 1
	v_permlane32_swap_b32_e32 v251, v252
	v_max_f32_e32 v251, v251, v252
	v_cmp_lt_f32_e32 vcc, 0x41000000, v251
	s_cmp_lg_u32 s26, 0
	s_cbranch_scc0 .Lmla_nr1
	s_cbranch_vccnz .Lmla_rare1

; __device__ __forceinline__ void mla_unit(int h, int qb, const bf16_t* __restrict__ Qm, const bf16_t* __restrict__ Km, const bf16_t* __restrict__ Kr, const bf16_t* __restrict__ Vm, bf16_t* ZM, LAS char* lds) {
;     ...
;     for (int t = 0; t < NT; t += 2) {
;         MLA_STEP(t, gknA, gvA, gkrA, gknB, gvB, gkrB);
;         MLA_STEP(t + 1, gknB, gvB, gkrB, gknA, gvA, gkrA);
;     }
.Lmla_end1:
	s_add_i32 s65, s65, 2
	s_cmp_lt_u32 s65, s40
	s_cbranch_scc1 .Lmla_loop
	s_waitcnt vmcnt(3)
	s_branch .LBB0_741
.Lmla_skip0:
	s_waitcnt vmcnt(3)
	ds_write_b128 v205, v[120:123] offset:0
	ds_write_b128 v206, v[124:127] offset:38912
	ds_write_b128 v207, v[128:131] offset:128
	s_waitcnt lgkmcnt(0)
	s_barrier
	s_branch .Lmla_end0
.Lmla_mask0:
	v_sub_u32_e32 v0, v188, v208
	v_subrev_u32_e32 v0, s27, v0
	s_nop 0
	v_cmp_le_i32_e32 vcc, 0, v0
	v_cmp_le_i32_e64 s[6:7], 1, v0
	s_nop 0
	v_cndmask_b32_e32 v132, v204, v132, vcc
	v_cndmask_b32_e64 v133, v204, v133, s[6:7]
	v_cmp_le_i32_e32 vcc, 2, v0
	v_cmp_le_i32_e64 s[6:7], 3, v0
	s_nop 0
	v_cndmask_b32_e32 v134, v204, v134, vcc
	v_cndmask_b32_e64 v135, v204, v135, s[6:7]
	v_cmp_le_i32_e32 vcc, 8, v0
	v_cmp_le_i32_e64 s[6:7], 9, v0
	s_nop 0
	v_cndmask_b32_e32 v136, v204, v136, vcc
	v_cndmask_b32_e64 v137, v204, v137, s[6:7]
	v_cmp_le_i32_e32 vcc, 10, v0
	v_cmp_le_i32_e64 s[6:7], 11, v0
	s_nop 0
	v_cndmask_b32_e32 v138, v204, v138, vcc
	v_cndmask_b32_e64 v139, v204, v139, s[6:7]
	v_cmp_le_i32_e32 vcc, 16, v0
	v_cmp_le_i32_e64 s[6:7], 17, v0
	s_nop 0
	v_cndmask_b32_e32 v140, v204, v140, vcc
	v_cndmask_b32_e64 v141, v204, v141, s[6:7]
	v_cmp_le_i32_e32 vcc, 18, v0
	v_cmp_le_i32_e64 s[6:7], 19, v0
	s_nop 0
	v_cndmask_b32_e32 v142, v204, v142, vcc
	v_cndmask_b32_e64 v143, v204, v143, s[6:7]
	v_cmp_le_i32_e32 vcc, 24, v0
	v_cmp_le_i32_e64 s[6:7], 25, v0
	s_nop 0
	v_cndmask_b32_e32 v144, v204, v144, vcc
	v_cndmask_b32_e64 v145, v204, v145, s[6:7]
	v_cmp_le_i32_e32 vcc, 26, v0
	v_cmp_le_i32_e64 s[6:7], 27, v0
	s_nop 0
	v_cndmask_b32_e32 v146, v204, v146, vcc
	v_cndmask_b32_e64 v147, v204, v147, s[6:7]
	v_cmp_le_i32_e32 vcc, 32, v0
	v_cmp_le_i32_e64 s[6:7], 33, v0
	s_nop 0
	v_cndmask_b32_e32 v148, v204, v148, vcc
	v_cndmask_b32_e64 v149, v204, v149, s[6:7]
	v_cmp_le_i32_e32 vcc, 34, v0
	v_cmp_le_i32_e64 s[6:7], 35, v0
	s_nop 0
	v_cndmask_b32_e32 v150, v204, v150, vcc
	v_cndmask_b32_e64 v151, v204, v151, s[6:7]
	v_cmp_le_i32_e32 vcc, 40, v0
	v_cmp_le_i32_e64 s[6:7], 41, v0
	s_nop 0
	v_cndmask_b32_e32 v152, v204, v152, vcc
	v_cndmask_b32_e64 v153, v204, v153, s[6:7]
	v_cmp_le_i32_e32 vcc, 42, v0
	v_cmp_le_i32_e64 s[6:7], 43, v0
	s_nop 0
	v_cndmask_b32_e32 v154, v204, v154, vcc
	v_cndmask_b32_e64 v155, v204, v155, s[6:7]
	v_cmp_le_i32_e32 vcc, 48, v0
	v_cmp_le_i32_e64 s[6:7], 49, v0
	s_nop 0
	v_cndmask_b32_e32 v156, v204, v156, vcc
	v_cndmask_b32_e64 v157, v204, v157, s[6:7]
	v_cmp_le_i32_e32 vcc, 50, v0
	v_cmp_le_i32_e64 s[6:7], 51, v0
	s_nop 0
	v_cndmask_b32_e32 v158, v204, v158, vcc
	v_cndmask_b32_e64 v159, v204, v159, s[6:7]
	v_cmp_le_i32_e32 vcc, 56, v0
	v_cmp_le_i32_e64 s[6:7], 57, v0
	s_nop 0
	v_cndmask_b32_e32 v160, v204, v160, vcc
	v_cndmask_b32_e64 v161, v204, v161, s[6:7]
	v_cmp_le_i32_e32 vcc, 58, v0
	v_cmp_le_i32_e64 s[6:7], 59, v0
	s_nop 0
	v_cndmask_b32_e32 v162, v204, v162, vcc
	v_cndmask_b32_e64 v163, v204, v163, s[6:7]
	s_branch .Lmla_maskret0
.Lmla_rare0:
	s_nop 7
	s_nop 4
	v_max_f32_e32 v253, 0, v251
	v_add_f32_e32 v212, v212, v253
	v_exp_f32_e64 v252, -v253
	v_xor_b32_e32 v48, 0x80000000, v212
	v_sub_f32_e32 v132, v132, v253
	v_sub_f32_e32 v133, v133, v253
	v_sub_f32_e32 v134, v134, v253
	v_sub_f32_e32 v135, v135, v253
	v_sub_f32_e32 v136, v136, v253
	v_sub_f32_e32 v137, v137, v253
	v_sub_f32_e32 v138, v138, v253
	v_sub_f32_e32 v139, v139, v253
	v_sub_f32_e32 v140, v140, v253
	v_sub_f32_e32 v141, v141, v253
	v_sub_f32_e32 v142, v142, v253
	v_sub_f32_e32 v143, v143, v253
	v_sub_f32_e32 v144, v144, v253
	v_sub_f32_e32 v145, v145, v253
	v_sub_f32_e32 v146, v146, v253
	v_sub_f32_e32 v147, v147, v253
	v_sub_f32_e32 v148, v148, v253
	v_sub_f32_e32 v149, v149, v253
	v_sub_f32_e32 v150, v150, v253
	v_sub_f32_e32 v151, v151, v253
	v_sub_f32_e32 v152, v152, v253
	v_sub_f32_e32 v153, v153, v253
	v_sub_f32_e32 v154, v154, v253
	v_sub_f32_e32 v155, v155, v253
	v_sub_f32_e32 v156, v156, v253
	v_sub_f32_e32 v157, v157, v253
	v_sub_f32_e32 v158, v158, v253
	v_sub_f32_e32 v159, v159, v253
	v_sub_f32_e32 v160, v160, v253
	v_sub_f32_e32 v161, v161, v253
	v_sub_f32_e32 v162, v162, v253
	v_sub_f32_e32 v163, v163, v253
	v_mov_b32_e32 v49, v48
	v_mov_b32_e32 v50, v48
	v_mov_b32_e32 v51, v48
	v_mov_b32_e32 v52, v48
	v_mov_b32_e32 v53, v48
	v_mov_b32_e32 v54, v48
	v_mov_b32_e32 v55, v48
	v_mov_b32_e32 v56, v48
	v_mov_b32_e32 v57, v48
	v_mov_b32_e32 v58, v48
	v_mov_b32_e32 v59, v48
	v_mov_b32_e32 v60, v48
	v_mov_b32_e32 v61, v48
	v_mov_b32_e32 v62, v48
	v_mov_b32_e32 v63, v48
	v_mul_f32_e32 v32, v32, v252
	v_mul_f32_e32 v33, v33, v252
	v_mul_f32_e32 v34, v34, v252
	v_mul_f32_e32 v35, v35, v252
	v_mul_f32_e32 v36, v36, v252
	v_mul_f32_e32 v37, v37, v252
	v_mul_f32_e32 v38, v38, v252
	v_mul_f32_e32 v39, v39, v252
	v_mul_f32_e32 v40, v40, v252
	v_mul_f32_e32 v41, v41, v252
	v_mul_f32_e32 v42, v42, v252
	v_mul_f32_e32 v43, v43, v252
	v_mul_f32_e32 v44, v44, v252
	v_mul_f32_e32 v45, v45, v252
	v_mul_f32_e32 v46, v46, v252
	v_mul_f32_e32 v47, v47, v252
	v_mul_f32_e32 v16, v16, v252
	v_mul_f32_e32 v17, v17, v252
	v_mul_f32_e32 v18, v18, v252
	v_mul_f32_e32 v19, v19, v252
	v_mul_f32_e32 v20, v20, v252
	v_mul_f32_e32 v21, v21, v252
	v_mul_f32_e32 v22, v22, v252
	v_mul_f32_e32 v23, v23, v252
	v_mul_f32_e32 v24, v24, v252
	v_mul_f32_e32 v25, v25, v252
	v_mul_f32_e32 v26, v26, v252
	v_mul_f32_e32 v27, v27, v252
	v_mul_f32_e32 v28, v28, v252
	v_mul_f32_e32 v29, v29, v252
	v_mul_f32_e32 v30, v30, v252
	v_mul_f32_e32 v31, v31, v252
	v_mul_f32_e32 v209, v209, v252
	s_branch .Lmla_nr0
.Lmla_skip1:
	s_waitcnt vmcnt(3)
	ds_write_b128 v205, v[6:9] offset:25600
	ds_write_b128 v206, v[10:13] offset:13312
	ds_write_b128 v207, v[2:5] offset:25728
	s_waitcnt lgkmcnt(0)
	s_barrier
	s_branch .Lmla_end1
.Lmla_mask1:
	v_sub_u32_e32 v0, v188, v208
	v_subrev_u32_e32 v0, s27, v0
	s_nop 0
	v_cmp_le_i32_e32 vcc, 0, v0
	v_cmp_le_i32_e64 s[6:7], 1, v0
	s_nop 0
	v_cndmask_b32_e32 v64, v204, v64, vcc
	v_cndmask_b32_e64 v65, v204, v65, s[6:7]
	v_cmp_le_i32_e32 vcc, 2, v0
	v_cmp_le_i32_e64 s[6:7], 3, v0
	s_nop 0
	v_cndmask_b32_e32 v66, v204, v66, vcc
	v_cndmask_b32_e64 v67, v204, v67, s[6:7]
	v_cmp_le_i32_e32 vcc, 8, v0
	v_cmp_le_i32_e64 s[6:7], 9, v0
	s_nop 0
	v_cndmask_b32_e32 v68, v204, v68, vcc
	v_cndmask_b32_e64 v69, v204, v69, s[6:7]
	v_cmp_le_i32_e32 vcc, 10, v0
	v_cmp_le_i32_e64 s[6:7], 11, v0
	s_nop 0
	v_cndmask_b32_e32 v70, v204, v70, vcc
	v_cndmask_b32_e64 v71, v204, v71, s[6:7]
	v_cmp_le_i32_e32 vcc, 16, v0
	v_cmp_le_i32_e64 s[6:7], 17, v0
	s_nop 0
	v_cndmask_b32_e32 v72, v204, v72, vcc
	v_cndmask_b32_e64 v73, v204, v73, s[6:7]
	v_cmp_le_i32_e32 vcc, 18, v0
	v_cmp_le_i32_e64 s[6:7], 19, v0
	s_nop 0
	v_cndmask_b32_e32 v74, v204, v74, vcc
	v_cndmask_b32_e64 v75, v204, v75, s[6:7]
	v_cmp_le_i32_e32 vcc, 24, v0
	v_cmp_le_i32_e64 s[6:7], 25, v0
	s_nop 0
	v_cndmask_b32_e32 v76, v204, v76, vcc
	v_cndmask_b32_e64 v77, v204, v77, s[6:7]
	v_cmp_le_i32_e32 vcc, 26, v0
	v_cmp_le_i32_e64 s[6:7], 27, v0
	s_nop 0
	v_cndmask_b32_e32 v78, v204, v78, vcc
	v_cndmask_b32_e64 v79, v204, v79, s[6:7]
	v_cmp_le_i32_e32 vcc, 32, v0
	v_cmp_le_i32_e64 s[6:7], 33, v0
	s_nop 0
	v_cndmask_b32_e32 v80, v204, v80, vcc
	v_cndmask_b32_e64 v81, v204, v81, s[6:7]
	v_cmp_le_i32_e32 vcc, 34, v0
	v_cmp_le_i32_e64 s[6:7], 35, v0
	s_nop 0
	v_cndmask_b32_e32 v82, v204, v82, vcc
	v_cndmask_b32_e64 v83, v204, v83, s[6:7]
	v_cmp_le_i32_e32 vcc, 40, v0
	v_cmp_le_i32_e64 s[6:7], 41, v0
	s_nop 0
	v_cndmask_b32_e32 v84, v204, v84, vcc
	v_cndmask_b32_e64 v85, v204, v85, s[6:7]
	v_cmp_le_i32_e32 vcc, 42, v0
	v_cmp_le_i32_e64 s[6:7], 43, v0
	s_nop 0
	v_cndmask_b32_e32 v86, v204, v86, vcc
	v_cndmask_b32_e64 v87, v204, v87, s[6:7]
	v_cmp_le_i32_e32 vcc, 48, v0
	v_cmp_le_i32_e64 s[6:7], 49, v0
	s_nop 0
	v_cndmask_b32_e32 v88, v204, v88, vcc
	v_cndmask_b32_e64 v89, v204, v89, s[6:7]
	v_cmp_le_i32_e32 vcc, 50, v0
	v_cmp_le_i32_e64 s[6:7], 51, v0
	s_nop 0
	v_cndmask_b32_e32 v90, v204, v90, vcc
	v_cndmask_b32_e64 v91, v204, v91, s[6:7]
	v_cmp_le_i32_e32 vcc, 56, v0
	v_cmp_le_i32_e64 s[6:7], 57, v0
	s_nop 0
	v_cndmask_b32_e32 v92, v204, v92, vcc
	v_cndmask_b32_e64 v93, v204, v93, s[6:7]
	v_cmp_le_i32_e32 vcc, 58, v0
	v_cmp_le_i32_e64 s[6:7], 59, v0
	s_nop 0
	v_cndmask_b32_e32 v94, v204, v94, vcc
	v_cndmask_b32_e64 v95, v204, v95, s[6:7]
	s_branch .Lmla_maskret1
.Lmla_rare1:
	s_nop 7
	s_nop 4
	v_max_f32_e32 v253, 0, v251
	v_add_f32_e32 v212, v212, v253
	v_exp_f32_e64 v252, -v253
	v_xor_b32_e32 v48, 0x80000000, v212
	v_sub_f32_e32 v64, v64, v253
	v_sub_f32_e32 v65, v65, v253
	v_sub_f32_e32 v66, v66, v253
	v_sub_f32_e32 v67, v67, v253
	v_sub_f32_e32 v68, v68, v253
	v_sub_f32_e32 v69, v69, v253
	v_sub_f32_e32 v70, v70, v253
	v_sub_f32_e32 v71, v71, v253
	v_sub_f32_e32 v72, v72, v253
	v_sub_f32_e32 v73, v73, v253
	v_sub_f32_e32 v74, v74, v253
	v_sub_f32_e32 v75, v75, v253
	v_sub_f32_e32 v76, v76, v253
	v_sub_f32_e32 v77, v77, v253
	v_sub_f32_e32 v78, v78, v253
	v_sub_f32_e32 v79, v79, v253
	v_sub_f32_e32 v80, v80, v253
	v_sub_f32_e32 v81, v81, v253
	v_sub_f32_e32 v82, v82, v253
	v_sub_f32_e32 v83, v83, v253
	v_sub_f32_e32 v84, v84, v253
	v_sub_f32_e32 v85, v85, v253
	v_sub_f32_e32 v86, v86, v253
	v_sub_f32_e32 v87, v87, v253
	v_sub_f32_e32 v88, v88, v253
	v_sub_f32_e32 v89, v89, v253
	v_sub_f32_e32 v90, v90, v253
	v_sub_f32_e32 v91, v91, v253
	v_sub_f32_e32 v92, v92, v253
	v_sub_f32_e32 v93, v93, v253
	v_sub_f32_e32 v94, v94, v253
	v_sub_f32_e32 v95, v95, v253
	v_mov_b32_e32 v49, v48
	v_mov_b32_e32 v50, v48
	v_mov_b32_e32 v51, v48
	v_mov_b32_e32 v52, v48
	v_mov_b32_e32 v53, v48
	v_mov_b32_e32 v54, v48
	v_mov_b32_e32 v55, v48
	v_mov_b32_e32 v56, v48
	v_mov_b32_e32 v57, v48
	v_mov_b32_e32 v58, v48
	v_mov_b32_e32 v59, v48
	v_mov_b32_e32 v60, v48
	v_mov_b32_e32 v61, v48
	v_mov_b32_e32 v62, v48
	v_mov_b32_e32 v63, v48
	v_mul_f32_e32 v32, v32, v252
	v_mul_f32_e32 v33, v33, v252
	v_mul_f32_e32 v34, v34, v252
	v_mul_f32_e32 v35, v35, v252
	v_mul_f32_e32 v36, v36, v252
	v_mul_f32_e32 v37, v37, v252
	v_mul_f32_e32 v38, v38, v252
	v_mul_f32_e32 v39, v39, v252
	v_mul_f32_e32 v40, v40, v252
	v_mul_f32_e32 v41, v41, v252
	v_mul_f32_e32 v42, v42, v252
	v_mul_f32_e32 v43, v43, v252
	v_mul_f32_e32 v44, v44, v252
	v_mul_f32_e32 v45, v45, v252
	v_mul_f32_e32 v46, v46, v252
	v_mul_f32_e32 v47, v47, v252
	v_mul_f32_e32 v16, v16, v252
	v_mul_f32_e32 v17, v17, v252
	v_mul_f32_e32 v18, v18, v252
	v_mul_f32_e32 v19, v19, v252
	v_mul_f32_e32 v20, v20, v252
	v_mul_f32_e32 v21, v21, v252
	v_mul_f32_e32 v22, v22, v252
	v_mul_f32_e32 v23, v23, v252
	v_mul_f32_e32 v24, v24, v252
	v_mul_f32_e32 v25, v25, v252
	v_mul_f32_e32 v26, v26, v252
	v_mul_f32_e32 v27, v27, v252
	v_mul_f32_e32 v28, v28, v252
	v_mul_f32_e32 v29, v29, v252
	v_mul_f32_e32 v30, v30, v252
	v_mul_f32_e32 v31, v31, v252
	v_mul_f32_e32 v209, v209, v252
	s_branch .Lmla_nr1
